# placement trial: all code after the prologue shifted by 8 bytes (two s_nop 0 before the layer loop); otherwise identical to the previous best
# speedup vs baseline: 1.0058x; 1.0058x over previous
; #define LAS __attribute__((address_space(3)))
; #define LANE_ASM(l_) asm volatile("v_mbcnt_lo_u32_b32 %0, -1, 0\n\tv_mbcnt_hi_u32_b32 %0, -1, %0" : "=v"(l_) :: "memory")
;     __device__ __forceinline__ unsigned char* ws() const { return (unsigned char*)(__attribute__((address_space(1))) unsigned char*)ld64(25); }
; #define GRID_SYNC_CG() do { asm volatile("s_waitcnt vmcnt(0) lgkmcnt(0)" ::: "memory"); grid.sync(); __builtin_amdgcn_fence(__ATOMIC_ACQUIRE, "agent"); asm volatile("s_waitcnt vmcnt(0)" ::: "memory"); } while (0)
; __global__ void __launch_bounds__(NTHREADS, 2) mega_fwd(Args a_unused) {
;     ...
;     Ctx a{lds};
;     prologue(a, lds, wave_s);
;     GRID_SYNC_CG();
;     { int l_; LANE_ASM(l_); (void)xcd_barrier_post((unsigned*)(a.ws() + WS_XBAR), (volatile LAS unsigned*)(lds + PTAB_OFF + 256), wave_s == 0 && l_ == 0); }
;     _Pragma("unroll") for (int layer = 0; layer < 4; ++layer) {
;         if (layer == 0) rowpass(a, true, false, 0, 0, 0, true, 6, 0, 1024, 0, layer, wave_s);
;         else rowpass(a, false, true, 9, layer - 1, 5120 - NB * 6144, true, 6, layer, 1024, 0, layer, wave_s);
.LBB0_104:
	s_or_b64 exec, exec, s[0:1]
	s_bfe_u32 s47, s3, 0x20006
	s_lshl_b32 s0, s47, 14
	s_add_i32 s0, s0, 0
	v_writelane_b32 v255, s0, 4
	s_lshl_b32 s0, s47, 5
	v_writelane_b32 v255, s0, 5
	s_lshr_b32 s2, s3, 8
	v_readlane_b32 s4, v255, 0
	s_lshl_b32 s1, s4, 2
	s_add_i32 s1, s1, 0
	s_lshl_b32 s0, s2, 6
	s_add_i32 s1, s1, 0x16800
	s_cmpk_lt_u32 s3, 0x100
	s_cselect_b64 s[14:15], -1, 0
	s_cmpk_gt_u32 s3, 0xff
	v_writelane_b32 v255, s1, 6
	s_cselect_b64 s[6:7], -1, 0
	v_writelane_b32 v255, s6, 7
	s_cmp_eq_u32 s2, 1
	s_mul_i32 s9, s63, s62
	v_writelane_b32 v255, s7, 8
	v_writelane_b32 v255, s2, 9
	s_cselect_b64 s[6:7], -1, 0
	v_writelane_b32 v255, s6, 10
	s_lshr_b32 s1, s3, 7
	s_lshl_b32 s56, s0, 1
	v_writelane_b32 v255, s7, 11
	v_writelane_b32 v255, s1, 12
	s_lshl_b32 s1, s4, 5
	s_and_b32 s2, s1, 32
	v_writelane_b32 v255, s2, 13
	s_lshl_b32 s2, s4, 9
	s_ashr_i32 s3, s2, 31
	v_writelane_b32 v255, s2, 14
	s_and_b32 s1, s1, 0x60
	s_add_i32 s0, 0, 0x16810
	v_writelane_b32 v255, s3, 15
	s_addk_i32 s2, 0xf800
	s_mov_b32 s3, s11
	v_writelane_b32 v255, s2, 16
	s_mul_i32 s9, s9, s18
	s_mov_b32 s55, 0xffff0000
	v_writelane_b32 v255, s3, 17
	v_writelane_b32 v255, s1, 18
	s_lshl_b32 s1, s4, 11
	v_writelane_b32 v255, s1, 19
	s_and_b32 s1, s1, 0x7fffe000
	s_add_i32 s1, s1, 0
	v_writelane_b32 v255, s1, 20
	s_lshl_b32 s1, s4, 3
	s_and_b32 s54, s1, 0x1fffffe0
	s_add_i32 s1, 0, 0x20048
	v_writelane_b32 v255, s1, 21
	s_add_i32 s1, 0, 0x20030
	v_writelane_b32 v255, s1, 22
	s_add_i32 s1, 0, 0x200c0
	v_writelane_b32 v255, s1, 23
	s_add_i32 s1, 0, 0x20000
	v_writelane_b32 v255, s1, 24
	s_add_i32 s1, 0, 0x20100
	v_writelane_b32 v255, s1, 25
	s_add_i32 s1, 0, 0x20104
	v_writelane_b32 v255, s1, 26
	s_add_i32 s1, 0, 0x200a8
	v_writelane_b32 v255, s1, 27
	s_add_i32 s1, 0, 0x16820
	v_writelane_b32 v255, s1, 28
	v_writelane_b32 v255, s0, 29
	s_add_i32 s0, 0, 0x200a0
	v_writelane_b32 v255, s0, 30
	s_add_i32 s0, 0, 0x20088
	v_writelane_b32 v255, s0, 31
	s_add_i32 s0, 0, 0x20038
	v_writelane_b32 v255, s0, 32
	v_writelane_b32 v255, s85, 33
	s_mov_b32 s0, s62
	s_lshl_b32 s2, s4, 10
	v_writelane_b32 v255, s0, 34
	s_add_i32 s52, s2, 0
	v_mov_b32_e32 v196, 0x358637bd
	s_mov_b32 s3, 0xf800000
	v_mov_b32_e32 v197, 0x260
	s_movk_i32 s48, 0x7fff
	v_mov_b32_e32 v1, 0
	v_mov_b32_e32 v198, 0x1000
	v_mov_b32_e32 v199, 0x2000
	v_mov_b32_e32 v201, 1
	s_mov_b32 s19, 0x42800000
	v_mov_b32_e32 v177, 0x426c0000
	v_mov_b64_e32 v[178:179], 0xf00
	v_mov_b64_e32 v[180:181], 0xeff
	v_mov_b32_e32 v202, 0x42800000
	v_mov_b32_e32 v203, 0xf149f2ca
	v_mov_b32_e32 v204, 0x7f800000
	v_mov_b32_e32 v205, 0x80
	v_mov_b32_e32 v254, 0xf00
	v_mov_b32_e32 v200, 0x8000
	v_mov_b32_e32 v208, 0xf0000
	v_mov_b32_e32 v209, 0x800000
	v_mov_b32_e32 v210, 0xf000000
	v_bfrev_b32_e32 v211, 1
	v_mov_b64_e32 v[182:183], 0x500
	v_mov_b64_e32 v[184:185], 0x4ff
	v_mov_b64_e32 v[186:187], 0x13ff
	s_mov_b32 s53, 0xff61b1e6
	s_mov_b32 s22, 0x40c00000
	s_add_i32 s21, 0, 0x20070
	s_mov_b32 s33, 0x43000000
	s_movk_i32 s46, 0xa1
	s_mov_b32 s17, 0x40000
	s_mov_b32 s50, 0x48000
	s_mov_b32 s20, 0x50000
	s_mov_b32 s49, 0x58000
	s_mov_b64 s[60:61], 0x800
	s_mov_b64 s[64:65], 0x1000
	s_mov_b64 s[66:67], 0x40000
	s_mov_b64 s[68:69], 0x80
	s_mov_b64 s[70:71], 0x2000
	s_mov_b32 s76, 0x3e38aa3b
	s_mov_b64 s[78:79], 0x48000
	s_mov_b64 s[80:81], 0x50000
	s_mov_b64 s[82:83], 0x58000
	s_mov_b32 s84, s11
	v_writelane_b32 v255, s1, 35
	s_nop 0
	s_nop 0
	s_branch .LBB0_107
